# UC phase: each lane takes two neighbouring partial-sum slots, 8-byte partial-sum loads (13 loads per token instead of 21)
# baseline (speedup 1.0000x reference)
; DI void phase_peer_u(const Args& a, int layer, int ci) {
;     ...
;             const int mn = m + NGW < M ? m + NGW : m;
;             const int idAn = IDX[(size_t)mn * 128 + lane], idBn = IDX[(size_t)mn * 128 + 64 + lane];
;             const u32x4 xan = *(const u32x4*)(XN + (size_t)mn * D), xbn = *(const u32x4*)(XN + (size_t)mn * D + 8);
;             float glA = 0.f, glB = 0.f, pdA = 0.f, pdB = 0.f, rstdu = 0.f;
;             if (ci == 1) {
;                 glA = GATE[(size_t)m * 128 + lane] * GSUM[(size_t)m * 8 + (lane >> 4)] * (1.f / V_SCALE);
;                 glB = GATE[(size_t)m * 128 + 64 + lane] * GSUM[(size_t)m * 8 + 4 + (lane >> 4)] * (1.f / V_SCALE);
;                 pdA = PD[(size_t)m * 128 + lane]; pdB = PD[(size_t)m * 128 + 64 + lane];
;                 rstdu = __builtin_bit_cast(float, __builtin_amdgcn_readfirstlane(__builtin_bit_cast(int, rsqrtf(wave_sum(lane < 32 ? ((const float*)(ws + WS_RSS))[((size_t)layer * M + m) * 32 + lane] : 0.f) * (1.f / D) + 1e-6f) * (1.f / U_SCALE))));
.Lpuc_entry:
	v_readlane_b32 s1, v252, 0
	v_readlane_b32 s19, v255, 12
	v_lshrrev_b32_e32 v5, 6, v185
	v_and_b32_e32 v6, 63, v185
	v_lshlrev_b32_e32 v0, 3, v6
	v_and_b32_e32 v1, 31, v6
	v_lshlrev_b32_e32 v1, 2, v1
	v_lshrrev_b32_e32 v3, 4, v6
	v_and_b32_e32 v4, 1, v6
	v_lshl_or_b32 v3, v3, 1, v4
	v_bfe_u32 v7, v6, 1, 3
	v_lshl_or_b32 v2, v3, 4, v7
	v_lshlrev_b32_e32 v2, 2, v2
	v_lshlrev_b32_e32 v3, 2, v3
	v_readfirstlane_b32 s44, v5
	s_lshl_b32 s45, s1, 3
	s_add_u32 s45, s45, s44
	s_lshl_b32 s46, s45, 13
	s_add_u32 s46, s46, 0x20000000
	s_add_u32 s38, s98, s46
	s_addc_u32 s39, s99, 0
	s_lshl_b32 s46, s45, 13
	s_add_u32 s46, s46, 0x7000000
	s_add_u32 s42, s98, s46
	s_addc_u32 s43, s99, 0
	s_mov_b64 s[16:17], s[42:43]
	s_lshl_b32 s46, s19, 22
	s_lshl_b32 s47, s45, 11
	s_add_u32 s46, s46, s47
	s_add_u32 s46, s46, 0xd800000
	s_add_u32 s40, s98, s46
	s_addc_u32 s41, s99, 0
	s_lshl_b32 s46, s45, 9
	s_add_u32 s46, s46, 0x5e00000
	s_add_u32 s24, s98, s46
	s_addc_u32 s25, s99, 0
	s_mov_b32 s101, 0x39800000
	s_mov_b32 s19, 0x3d372713
	s_mov_b32 s100, 0x200
	s_mov_b32 s0, 0
	s_add_u32 s22, s38, 0x1000000
	s_addc_u32 s23, s39, 0
	global_load_dwordx2 v[8:9], v0, s[22:23]
	s_add_u32 s22, s22, 0x2000000
	s_addc_u32 s23, s23, 0
	global_load_dwordx2 v[10:11], v0, s[22:23]
	s_add_u32 s22, s22, 0x2000000
	s_addc_u32 s23, s23, 0
	global_load_dwordx2 v[12:13], v0, s[22:23]
	s_add_u32 s22, s22, 0x2000000
	s_addc_u32 s23, s23, 0
	global_load_dwordx2 v[14:15], v0, s[22:23]
	s_add_u32 s22, s22, 0x2000000
	s_addc_u32 s23, s23, 0
	global_load_dwordx2 v[16:17], v0, s[22:23]
	s_add_u32 s22, s22, 0x2000000
	s_addc_u32 s23, s23, 0
	global_load_dwordx2 v[18:19], v0, s[22:23]
	s_add_u32 s22, s22, 0x2000000
	s_addc_u32 s23, s23, 0
	global_load_dwordx2 v[20:21], v0, s[22:23]
	s_add_u32 s22, s22, 0x2000000
	s_addc_u32 s23, s23, 0
	global_load_dwordx2 v[22:23], v0, s[22:23]
	global_load_dword v40, v1, s[40:41]
	global_load_dword v41, v2, s[42:43]
	global_load_dword v42, v2, s[42:43] offset:32
	global_load_dword v43, v3, s[24:25]
	global_load_dword v44, v3, s[24:25]
; DI void phase_peer_u(const Args& a, int layer, int ci) {
;     ...
;             if (ci == 1) {
;                 glA = GATE[(size_t)m * 128 + lane] * GSUM[(size_t)m * 8 + (lane >> 4)] * (1.f / V_SCALE);
;                 glB = GATE[(size_t)m * 128 + 64 + lane] * GSUM[(size_t)m * 8 + 4 + (lane >> 4)] * (1.f / V_SCALE);
;                 pdA = PD[(size_t)m * 128 + lane]; pdB = PD[(size_t)m * 128 + 64 + lane];
;                 rstdu = __builtin_bit_cast(float, __builtin_amdgcn_readfirstlane(__builtin_bit_cast(int, rsqrtf(wave_sum(lane < 32 ? ((const float*)(ws + WS_RSS))[((size_t)layer * M + m) * 32 + lane] : 0.f) * (1.f / D) + 1e-6f) * (1.f / U_SCALE))));
;             }
;             float rA = 0.f, rB = 0.f;
; #pragma unroll 1
;             for (int g8 = 0; g8 < 16; ++g8) {
;                 u32x4 nxt[8];
;                 if (g8 < 15) gat_loadhu(U, idA, idB, g8 + 1, lo16, nxt); else gat_loadhu(U, idAn, idBn, 0, lo16, nxt);
;                 const float c0 = dots4h(xa, xb, cur[0], cur[1], cur[2], cur[3], lane);
;                 const float c1 = dots4h(xa, xb, cur[4], cur[5], cur[6], cur[7], lane);
;                 const int q4 = (g8 & 7) * 2;
;                 const float cv = (lane >> 2) == q4 ? c0 : c1;
;                 const bool mine = (lane >> 3) == (g8 & 7);
;                 if (ci == 0) { if (g8 < 8) rA = mine ? cv : rA; else rB = mine ? cv : rB; }
;                 else { if (g8 < 8) rA = mine ? gelu_tanh((cv + pdA) * rstdu) * glA : rA; else rB = mine ? gelu_tanh((cv + pdB) * rstdu) * glB : rB; }
; #pragma unroll
;                 for (int j = 0; j < 8; ++j) cur[j] = nxt[j];
;             }
;             if (ci == 0) { PD[(size_t)m * 128 + lane] = rA; PD[(size_t)m * 128 + 64 + lane] = rB; }
;             else { GATE[(size_t)m * 128 + lane] = rA; GATE[(size_t)m * 128 + 64 + lane] = rB; }
.Lpuc_loop:
	s_add_u32 s38, s38, s100
	s_addc_u32 s39, s39, 0
	s_lshr_b32 s44, s100, 2
	s_add_u32 s40, s40, s44
	s_addc_u32 s41, s41, 0
	s_lshr_b32 s44, s100, 4
	s_add_u32 s24, s24, s44
	s_addc_u32 s25, s25, 0
	s_add_u32 s42, s42, s100
	s_addc_u32 s43, s43, 0
	s_add_u32 s22, s38, 0x1000000
	s_addc_u32 s23, s39, 0
	global_load_dwordx2 v[56:57], v0, s[22:23]
	s_add_u32 s22, s22, 0x2000000
	s_addc_u32 s23, s23, 0
	global_load_dwordx2 v[58:59], v0, s[22:23]
	s_add_u32 s22, s22, 0x2000000
	s_addc_u32 s23, s23, 0
	global_load_dwordx2 v[60:61], v0, s[22:23]
	s_add_u32 s22, s22, 0x2000000
	s_addc_u32 s23, s23, 0
	global_load_dwordx2 v[62:63], v0, s[22:23]
	s_add_u32 s22, s22, 0x2000000
	s_addc_u32 s23, s23, 0
	global_load_dwordx2 v[64:65], v0, s[22:23]
	s_add_u32 s22, s22, 0x2000000
	s_addc_u32 s23, s23, 0
	global_load_dwordx2 v[66:67], v0, s[22:23]
	s_add_u32 s22, s22, 0x2000000
	s_addc_u32 s23, s23, 0
	global_load_dwordx2 v[68:69], v0, s[22:23]
	s_add_u32 s22, s22, 0x2000000
	s_addc_u32 s23, s23, 0
	global_load_dwordx2 v[70:71], v0, s[22:23]
	global_load_dword v88, v1, s[40:41]
	global_load_dword v89, v2, s[42:43]
	global_load_dword v90, v2, s[42:43] offset:32
	global_load_dword v91, v3, s[24:25]
	global_load_dword v92, v3, s[24:25]
	s_waitcnt vmcnt(13)
	v_add_f32_e32 v104, v8, v10
	v_add_f32_e32 v104, v104, v12
	v_add_f32_e32 v104, v104, v14
	v_add_f32_e32 v104, v104, v16
	v_add_f32_e32 v104, v104, v18
	v_add_f32_e32 v104, v104, v20
	v_add_f32_e32 v104, v104, v22
	v_add_f32_e32 v105, v9, v11
	v_add_f32_e32 v105, v105, v13
	v_add_f32_e32 v105, v105, v15
	v_add_f32_e32 v105, v105, v17
	v_add_f32_e32 v105, v105, v19
	v_add_f32_e32 v105, v105, v21
	v_add_f32_e32 v105, v105, v23
	v_mov_b32_e32 v106, v40
	s_nop 1
	v_add_f32_dpp v106, v106, v106 quad_perm:[1,0,3,2] row_mask:0xf bank_mask:0xf
	s_nop 1
	v_add_f32_dpp v106, v106, v106 quad_perm:[2,3,0,1] row_mask:0xf bank_mask:0xf
	s_nop 1
	v_add_f32_dpp v106, v106, v106 row_half_mirror row_mask:0xf bank_mask:0xf
	s_nop 1
	v_add_f32_dpp v106, v106, v106 row_mirror row_mask:0xf bank_mask:0xf
	s_nop 1
	v_readlane_b32 s44, v106, 0
	v_readlane_b32 s45, v106, 16
	v_readlane_b32 s46, v106, 32
	v_readlane_b32 s47, v106, 48
	s_nop 1
	v_mov_b32_e32 v107, s44
	v_add_f32_e32 v107, s45, v107
	v_add_f32_e32 v107, s46, v107
	v_add_f32_e32 v107, s47, v107
	v_fma_f32 v107, v107, s101, v190
	v_rsq_f32_e32 v107, v107
	s_nop 0
	v_mul_f32_e32 v107, 0x3b000000, v107
	v_mul_f32_e32 v108, 0x3c800000, v43
	v_mul_f32_e32 v109, 0x3c800000, v44
	v_mul_f32_e32 v108, v108, v41
	v_mul_f32_e32 v109, v109, v42
	v_mul_f32_e32 v104, v104, v107
	v_mul_f32_e32 v110, v104, v104
	v_mul_f32_e32 v110, v110, v104
	v_fma_f32 v110, v110, s19, v104
	v_mul_f32_e32 v110, 0x40135761, v110
	v_exp_f32_e32 v110, v110
	s_nop 0
	v_add_f32_e32 v110, 1.0, v110
	v_rcp_f32_e32 v110, v110
	s_nop 0
	v_fma_f32 v111, -v104, v110, v104
	v_mul_f32_e32 v111, v111, v108
	v_mul_f32_e32 v105, v105, v107
	v_mul_f32_e32 v112, v105, v105
	v_mul_f32_e32 v112, v112, v105
	v_fma_f32 v112, v112, s19, v105
	v_mul_f32_e32 v112, 0x40135761, v112
	v_exp_f32_e32 v112, v112
	s_nop 0
	v_add_f32_e32 v112, 1.0, v112
	v_rcp_f32_e32 v112, v112
	s_nop 0
	v_fma_f32 v113, -v105, v112, v105
	v_mul_f32_e32 v113, v113, v109
	global_store_dword v2, v111, s[16:17]
	global_store_dword v2, v113, s[16:17] offset:32
	s_add_u32 s16, s16, 0x200
	s_addc_u32 s17, s17, 0
	s_cmp_eq_u32 s0, 7
	s_cselect_b32 s100, 0, s100
	s_add_u32 s38, s38, s100
	s_addc_u32 s39, s39, 0
	s_lshr_b32 s44, s100, 2
	s_add_u32 s40, s40, s44
	s_addc_u32 s41, s41, 0
	s_lshr_b32 s44, s100, 4
	s_add_u32 s24, s24, s44
	s_addc_u32 s25, s25, 0
	s_add_u32 s42, s42, s100
	s_addc_u32 s43, s43, 0
	s_add_u32 s22, s38, 0x1000000
	s_addc_u32 s23, s39, 0
	global_load_dwordx2 v[8:9], v0, s[22:23]
	s_add_u32 s22, s22, 0x2000000
	s_addc_u32 s23, s23, 0
	global_load_dwordx2 v[10:11], v0, s[22:23]
	s_add_u32 s22, s22, 0x2000000
	s_addc_u32 s23, s23, 0
	global_load_dwordx2 v[12:13], v0, s[22:23]
	s_add_u32 s22, s22, 0x2000000
	s_addc_u32 s23, s23, 0
	global_load_dwordx2 v[14:15], v0, s[22:23]
	s_add_u32 s22, s22, 0x2000000
	s_addc_u32 s23, s23, 0
	global_load_dwordx2 v[16:17], v0, s[22:23]
	s_add_u32 s22, s22, 0x2000000
	s_addc_u32 s23, s23, 0
	global_load_dwordx2 v[18:19], v0, s[22:23]
	s_add_u32 s22, s22, 0x2000000
	s_addc_u32 s23, s23, 0
	global_load_dwordx2 v[20:21], v0, s[22:23]
	s_add_u32 s22, s22, 0x2000000
	s_addc_u32 s23, s23, 0
	global_load_dwordx2 v[22:23], v0, s[22:23]
	global_load_dword v40, v1, s[40:41]
	global_load_dword v41, v2, s[42:43]
	global_load_dword v42, v2, s[42:43] offset:32
	global_load_dword v43, v3, s[24:25]
	global_load_dword v44, v3, s[24:25]
	s_waitcnt vmcnt(13)
	v_add_f32_e32 v104, v56, v58
	v_add_f32_e32 v104, v104, v60
	v_add_f32_e32 v104, v104, v62
	v_add_f32_e32 v104, v104, v64
	v_add_f32_e32 v104, v104, v66
	v_add_f32_e32 v104, v104, v68
	v_add_f32_e32 v104, v104, v70
	v_add_f32_e32 v105, v57, v59
	v_add_f32_e32 v105, v105, v61
	v_add_f32_e32 v105, v105, v63
	v_add_f32_e32 v105, v105, v65
	v_add_f32_e32 v105, v105, v67
	v_add_f32_e32 v105, v105, v69
	v_add_f32_e32 v105, v105, v71
	v_mov_b32_e32 v106, v88
	s_nop 1
	v_add_f32_dpp v106, v106, v106 quad_perm:[1,0,3,2] row_mask:0xf bank_mask:0xf
	s_nop 1
	v_add_f32_dpp v106, v106, v106 quad_perm:[2,3,0,1] row_mask:0xf bank_mask:0xf
	s_nop 1
	v_add_f32_dpp v106, v106, v106 row_half_mirror row_mask:0xf bank_mask:0xf
	s_nop 1
	v_add_f32_dpp v106, v106, v106 row_mirror row_mask:0xf bank_mask:0xf
	s_nop 1
	v_readlane_b32 s44, v106, 0
	v_readlane_b32 s45, v106, 16
	v_readlane_b32 s46, v106, 32
	v_readlane_b32 s47, v106, 48
	s_nop 1
	v_mov_b32_e32 v107, s44
	v_add_f32_e32 v107, s45, v107
	v_add_f32_e32 v107, s46, v107
	v_add_f32_e32 v107, s47, v107
	v_fma_f32 v107, v107, s101, v190
	v_rsq_f32_e32 v107, v107
	s_nop 0
	v_mul_f32_e32 v107, 0x3b000000, v107
	v_mul_f32_e32 v108, 0x3c800000, v91
	v_mul_f32_e32 v109, 0x3c800000, v92
	v_mul_f32_e32 v108, v108, v89
	v_mul_f32_e32 v109, v109, v90
	v_mul_f32_e32 v104, v104, v107
	v_mul_f32_e32 v110, v104, v104
	v_mul_f32_e32 v110, v110, v104
	v_fma_f32 v110, v110, s19, v104
	v_mul_f32_e32 v110, 0x40135761, v110
	v_exp_f32_e32 v110, v110
	s_nop 0
	v_add_f32_e32 v110, 1.0, v110
	v_rcp_f32_e32 v110, v110
	s_nop 0
	v_fma_f32 v111, -v104, v110, v104
	v_mul_f32_e32 v111, v111, v108
	v_mul_f32_e32 v105, v105, v107
	v_mul_f32_e32 v112, v105, v105
	v_mul_f32_e32 v112, v112, v105
	v_fma_f32 v112, v112, s19, v105
	v_mul_f32_e32 v112, 0x40135761, v112
	v_exp_f32_e32 v112, v112
	s_nop 0
	v_add_f32_e32 v112, 1.0, v112
	v_rcp_f32_e32 v112, v112
	s_nop 0
	v_fma_f32 v113, -v105, v112, v105
	v_mul_f32_e32 v113, v113, v109
	global_store_dword v2, v111, s[16:17]
	global_store_dword v2, v113, s[16:17] offset:32
	s_add_u32 s16, s16, 0x200
	s_addc_u32 s17, s17, 0
	s_add_u32 s0, s0, 1
	s_cmp_lt_u32 s0, 8
	s_cbranch_scc1 .Lpuc_loop
	s_waitcnt vmcnt(0)
	s_branch .LBB0_495
